# LayerNorm sample-row path: split-K partial sums read 16 loads (4 partials) at a time instead of 4*np serialised loads
# speedup vs baseline: 1.0237x; 1.0156x over previous
; DI float bflo(unsigned w) { return __uint_as_float(w << 16); }
; DI float bfhi(unsigned w) { return __uint_as_float(w & 0xffff0000u); }
; DI void ln_phase(LAS unsigned char* lds, const Args& a, int l, int mode) {
;     ...
;         if (row >= NPROMPT) { const int np = (mode == 2) ? 4 : 11; const float* pp = (const float*)(a.ws + WS_PART) + (size_t)(row - NPROMPT) * DM + 4 * lane;
; #pragma unroll
;             for (int i = 0; i < 4; ++i) { const u32x2 hb = *(const u32x2*)(XB + (size_t)row * DM + 256 * i + 4 * lane); x[i] = (f32x4){bflo(hb.x), bfhi(hb.x), bflo(hb.y), bfhi(hb.y)} * ALPHA; }
;             for (int p = 0; p < np; ++p) {
; #pragma unroll
;                 for (int i = 0; i < 4; ++i) x[i] += *(const f32x4*)(pp + (size_t)p * 256 * DM + 256 * i); } }
.LBB0_768:
	s_mov_b64 s[38:39], 0x100000
.Lpart_g4:
	s_cmp_lt_u32 s18, 4
	s_cbranch_scc1 .Lpart_tail
	global_load_dwordx4 v[100:103], v[82:83], off
	global_load_dwordx4 v[104:107], v[82:83], off offset:1024
	global_load_dwordx4 v[108:111], v[82:83], off offset:2048
	global_load_dwordx4 v[112:115], v[82:83], off offset:3072
	v_lshl_add_u64 v[82:83], v[82:83], 0, s[38:39]
	global_load_dwordx4 v[116:119], v[82:83], off
	global_load_dwordx4 v[120:123], v[82:83], off offset:1024
	global_load_dwordx4 v[124:127], v[82:83], off offset:2048
	global_load_dwordx4 v[180:183], v[82:83], off offset:3072
	v_lshl_add_u64 v[82:83], v[82:83], 0, s[38:39]
	global_load_dwordx4 v[184:187], v[82:83], off
	global_load_dwordx4 v[188:191], v[82:83], off offset:1024
	global_load_dwordx4 v[192:195], v[82:83], off offset:2048
	global_load_dwordx4 v[196:199], v[82:83], off offset:3072
	v_lshl_add_u64 v[82:83], v[82:83], 0, s[38:39]
	global_load_dwordx4 v[200:203], v[82:83], off
	global_load_dwordx4 v[204:207], v[82:83], off offset:1024
	global_load_dwordx4 v[208:211], v[82:83], off offset:2048
	global_load_dwordx4 v[212:215], v[82:83], off offset:3072
	v_lshl_add_u64 v[82:83], v[82:83], 0, s[38:39]
	s_waitcnt vmcnt(15)
	v_pk_add_f32 v[62:63], v[62:63], v[102:103]
	v_pk_add_f32 v[60:61], v[60:61], v[100:101]
	s_waitcnt vmcnt(14)
	v_pk_add_f32 v[58:59], v[58:59], v[106:107]
	v_pk_add_f32 v[56:57], v[56:57], v[104:105]
	s_waitcnt vmcnt(13)
	v_pk_add_f32 v[54:55], v[54:55], v[110:111]
	v_pk_add_f32 v[52:53], v[52:53], v[108:109]
	s_waitcnt vmcnt(12)
	v_pk_add_f32 v[50:51], v[50:51], v[114:115]
	v_pk_add_f32 v[48:49], v[48:49], v[112:113]
	s_waitcnt vmcnt(11)
	v_pk_add_f32 v[62:63], v[62:63], v[118:119]
	v_pk_add_f32 v[60:61], v[60:61], v[116:117]
	s_waitcnt vmcnt(10)
	v_pk_add_f32 v[58:59], v[58:59], v[122:123]
	v_pk_add_f32 v[56:57], v[56:57], v[120:121]
	s_waitcnt vmcnt(9)
	v_pk_add_f32 v[54:55], v[54:55], v[126:127]
	v_pk_add_f32 v[52:53], v[52:53], v[124:125]
	s_waitcnt vmcnt(8)
	v_pk_add_f32 v[50:51], v[50:51], v[182:183]
	v_pk_add_f32 v[48:49], v[48:49], v[180:181]
	s_waitcnt vmcnt(7)
	v_pk_add_f32 v[62:63], v[62:63], v[186:187]
	v_pk_add_f32 v[60:61], v[60:61], v[184:185]
	s_waitcnt vmcnt(6)
	v_pk_add_f32 v[58:59], v[58:59], v[190:191]
	v_pk_add_f32 v[56:57], v[56:57], v[188:189]
	s_waitcnt vmcnt(5)
	v_pk_add_f32 v[54:55], v[54:55], v[194:195]
	v_pk_add_f32 v[52:53], v[52:53], v[192:193]
	s_waitcnt vmcnt(4)
	v_pk_add_f32 v[50:51], v[50:51], v[198:199]
	v_pk_add_f32 v[48:49], v[48:49], v[196:197]
	s_waitcnt vmcnt(3)
	v_pk_add_f32 v[62:63], v[62:63], v[202:203]
	v_pk_add_f32 v[60:61], v[60:61], v[200:201]
	s_waitcnt vmcnt(2)
	v_pk_add_f32 v[58:59], v[58:59], v[206:207]
	v_pk_add_f32 v[56:57], v[56:57], v[204:205]
	s_waitcnt vmcnt(1)
	v_pk_add_f32 v[54:55], v[54:55], v[210:211]
	v_pk_add_f32 v[52:53], v[52:53], v[208:209]
	s_waitcnt vmcnt(0)
	v_pk_add_f32 v[50:51], v[50:51], v[214:215]
	v_pk_add_f32 v[48:49], v[48:49], v[212:213]
	s_add_i32 s18, s18, -4
	s_branch .Lpart_g4
.Lpart_tail:
	s_cmp_eq_u32 s18, 0
	s_cbranch_scc1 .Lpart_done
.Lpart_t1:
	global_load_dwordx4 v[100:103], v[82:83], off
	global_load_dwordx4 v[104:107], v[82:83], off offset:1024
	global_load_dwordx4 v[108:111], v[82:83], off offset:2048
	global_load_dwordx4 v[112:115], v[82:83], off offset:3072
	v_lshl_add_u64 v[82:83], v[82:83], 0, s[38:39]
	s_add_i32 s18, s18, -1
	s_waitcnt vmcnt(3)
	v_pk_add_f32 v[62:63], v[62:63], v[102:103]
	v_pk_add_f32 v[60:61], v[60:61], v[100:101]
	s_waitcnt vmcnt(2)
	v_pk_add_f32 v[58:59], v[58:59], v[106:107]
	v_pk_add_f32 v[56:57], v[56:57], v[104:105]
	s_waitcnt vmcnt(1)
	v_pk_add_f32 v[54:55], v[54:55], v[110:111]
	v_pk_add_f32 v[52:53], v[52:53], v[108:109]
	s_waitcnt vmcnt(0)
	v_pk_add_f32 v[50:51], v[50:51], v[114:115]
	v_pk_add_f32 v[48:49], v[48:49], v[112:113]
	s_cmp_lg_u32 s18, 0
	s_cbranch_scc1 .Lpart_t1
; DI unsigned pk2(float a, float b) { f32x2 v = {a, b}; nbf2 r = __builtin_convertvector(v, nbf2); return __builtin_bit_cast(unsigned, r); }
; DI void ln_phase(LAS unsigned char* lds, const Args& a, int l, int mode) {
;     ...
;         float s = 0.f;
; #pragma unroll
;         for (int i = 0; i < 4; ++i) s += (x[i][0] + x[i][1]) + (x[i][2] + x[i][3]);
;         const float mean = wave_sum(s) * (1.f / 1024.f);
;         float q = 0.f;
; #pragma unroll
;         for (int i = 0; i < 4; ++i) { x[i] = x[i] - mean; q += (x[i][0] * x[i][0] + x[i][1] * x[i][1]) + (x[i][2] * x[i][2] + x[i][3] * x[i][3]); }
;         const float rstd = rsqrtf(wave_sum(q) * (1.f / 1024.f) + 1e-5f);
; #pragma unroll
;         for (int i = 0; i < 4; ++i) { x[i] = x[i] * rstd * g4[i] + b4[i];
;             u32x2 w; w.x = pk2(x[i][0], x[i][1]); w.y = pk2(x[i][2], x[i][3]); *(u32x2*)(XB + (size_t)row * DM + 256 * i + 4 * lane) = w; }
.Lpart_done:
.LBB0_769:
	s_or_b64 exec, exec, s[36:37]
	v_mov_b32_e32 v82, v61
	v_mov_b32_e32 v83, v62
	v_mov_b32_e32 v92, v60
	v_mov_b32_e32 v93, v63
	v_pk_add_f32 v[82:83], v[82:83], v[92:93]
	v_mov_b32_e32 v92, v57
	v_mov_b32_e32 v93, v58
	v_mov_b32_e32 v94, v56
	v_mov_b32_e32 v95, v59
	v_pk_add_f32 v[92:93], v[92:93], v[94:95]
	v_add_f32_e32 v67, v82, v83
	v_pk_add_f32 v[92:93], v[92:93], v[92:93] op_sel_hi:[0,1]
	v_add_f32_e32 v83, 0, v67
	v_add_f32_e32 v95, v52, v53
	v_add_f32_e32 v97, v54, v55
	v_mov_b32_e32 v94, v48
	v_mov_b32_e32 v96, v49
	v_mov_b32_e32 v92, v50
	v_mov_b32_e32 v82, v51
	v_pk_add_f32 v[94:95], v[94:95], v[96:97]
	v_pk_add_f32 v[82:83], v[92:93], v[82:83]
	s_and_b64 s[18:19], exec, vcc
	v_pk_add_f32 v[82:83], v[94:95], v[82:83]
	s_or_b64 s[28:29], s[18:19], s[28:29]
	v_add_f32_e32 v67, v82, v83
	ds_bpermute_b32 v77, v85, v67
	s_waitcnt lgkmcnt(0)
	v_add_f32_e32 v67, v67, v77
	ds_bpermute_b32 v77, v86, v67
	s_waitcnt lgkmcnt(0)
	v_add_f32_e32 v67, v67, v77
	ds_bpermute_b32 v77, v87, v67
	s_waitcnt lgkmcnt(0)
	v_add_f32_e32 v67, v67, v77
	ds_bpermute_b32 v77, v88, v67
	s_waitcnt lgkmcnt(0)
	v_add_f32_e32 v67, v67, v77
	ds_bpermute_b32 v77, v89, v67
	s_waitcnt lgkmcnt(0)
	v_add_f32_e32 v67, v67, v77
	ds_bpermute_b32 v77, v90, v67
	s_waitcnt lgkmcnt(0)
	v_add_f32_e32 v67, v67, v77
	v_fmamk_f32 v61, v67, 0xba800000, v61
	v_fmamk_f32 v60, v67, 0xba800000, v60
	v_fmamk_f32 v63, v67, 0xba800000, v63
	v_fmamk_f32 v62, v67, 0xba800000, v62
	v_pk_mul_f32 v[82:83], v[62:63], v[62:63]
	v_pk_mul_f32 v[92:93], v[60:61], v[60:61]
	v_fmamk_f32 v57, v67, 0xba800000, v57
	v_pk_mov_b32 v[94:95], v[92:93], v[82:83] op_sel:[1,0]
	v_mov_b32_e32 v93, v83
	v_fmamk_f32 v56, v67, 0xba800000, v56
	v_fmamk_f32 v59, v67, 0xba800000, v59
	v_pk_add_f32 v[82:83], v[94:95], v[92:93]
	v_fmamk_f32 v58, v67, 0xba800000, v58
	v_pk_add_f32 v[82:83], v[82:83], v[82:83] op_sel_hi:[0,1]
	v_pk_mul_f32 v[92:93], v[58:59], v[58:59]
	v_pk_mul_f32 v[94:95], v[56:57], v[56:57]
	v_fmamk_f32 v52, v67, 0xba800000, v52
	v_pk_mov_b32 v[96:97], v[94:95], v[92:93] op_sel:[1,0]
	v_mov_b32_e32 v95, v93
	v_fmamk_f32 v53, v67, 0xba800000, v53
	v_fmamk_f32 v54, v67, 0xba800000, v54
	v_mul_f32_e32 v82, v52, v52
	v_pk_add_f32 v[92:93], v[96:97], v[94:95]
	v_fmamk_f32 v55, v67, 0xba800000, v55
	v_pk_fma_f32 v[94:95], v[52:53], v[52:53], v[82:83] op_sel_hi:[1,1,0]
	v_mul_f32_e32 v82, v54, v54
	v_pk_add_f32 v[92:93], v[92:93], v[92:93] op_sel_hi:[0,1]
	v_pk_fma_f32 v[96:97], v[54:55], v[54:55], v[82:83] op_sel_hi:[1,1,0]
	v_fmamk_f32 v51, v67, 0xba800000, v51
	v_fmamk_f32 v50, v67, 0xba800000, v50
	v_fmamk_f32 v49, v67, 0xba800000, v49
	v_fmac_f32_e32 v48, 0xba800000, v67
	v_mul_f32_e32 v94, v48, v48
	v_mul_f32_e32 v96, v49, v49
	v_mul_f32_e32 v82, v50, v50
	v_mul_f32_e32 v92, v51, v51
	v_pk_add_f32 v[94:95], v[94:95], v[96:97]
	v_pk_add_f32 v[82:83], v[82:83], v[92:93]
	s_nop 0
	v_pk_add_f32 v[82:83], v[94:95], v[82:83]
	s_nop 0
	v_add_f32_e32 v67, v82, v83
	ds_bpermute_b32 v77, v85, v67
	s_waitcnt lgkmcnt(0)
	v_add_f32_e32 v67, v67, v77
	ds_bpermute_b32 v77, v86, v67
	s_waitcnt lgkmcnt(0)
	v_add_f32_e32 v67, v67, v77
	ds_bpermute_b32 v77, v87, v67
	s_waitcnt lgkmcnt(0)
	v_add_f32_e32 v67, v67, v77
	ds_bpermute_b32 v77, v88, v67
	s_waitcnt lgkmcnt(0)
	v_add_f32_e32 v67, v67, v77
	ds_bpermute_b32 v77, v89, v67
	s_waitcnt lgkmcnt(0)
	v_add_f32_e32 v67, v67, v77
	ds_bpermute_b32 v77, v90, v67
	s_waitcnt lgkmcnt(0)
	v_add_f32_e32 v67, v67, v77
	v_fmamk_f32 v67, v67, 0x3a800000, v158
	v_mul_f32_e32 v77, 0x4b800000, v67
	v_cmp_gt_f32_e32 vcc, s46, v67
	s_nop 1
	v_cndmask_b32_e32 v67, v67, v77, vcc
	v_rsq_f32_e32 v67, v67
	s_nop 0
	v_mul_f32_e32 v77, 0x45800000, v67
	v_cndmask_b32_e32 v82, v67, v77, vcc
	v_pk_mul_f32 v[60:61], v[60:61], v[82:83] op_sel_hi:[1,0]
	v_pk_mul_f32 v[62:63], v[62:63], v[82:83] op_sel_hi:[1,0]
	v_pk_fma_f32 v[60:61], v[0:1], v[60:61], v[8:9]
	v_pk_fma_f32 v[62:63], v[2:3], v[62:63], v[10:11]
	v_pk_mul_f32 v[56:57], v[56:57], v[82:83] op_sel_hi:[1,0]
	v_pk_mul_f32 v[58:59], v[58:59], v[82:83] op_sel_hi:[1,0]
	v_cvt_pk_bf16_f32 v92, v60, v61
	v_cvt_pk_bf16_f32 v93, v62, v63
	v_pk_fma_f32 v[58:59], v[6:7], v[58:59], v[14:15]
	v_pk_fma_f32 v[56:57], v[4:5], v[56:57], v[12:13]
	v_pk_mul_f32 v[52:53], v[52:53], v[82:83] op_sel_hi:[1,0]
	v_pk_mul_f32 v[54:55], v[54:55], v[82:83] op_sel_hi:[1,0]
	v_pk_mul_f32 v[48:49], v[48:49], v[82:83] op_sel_hi:[1,0]
	v_pk_mul_f32 v[50:51], v[50:51], v[82:83] op_sel_hi:[1,0]
	global_store_dwordx2 v[80:81], v[92:93], off
	v_cvt_pk_bf16_f32 v92, v56, v57
	v_cvt_pk_bf16_f32 v93, v58, v59
	v_pk_fma_f32 v[54:55], v[18:19], v[54:55], v[26:27]
	v_pk_fma_f32 v[52:53], v[16:17], v[52:53], v[24:25]
	v_pk_fma_f32 v[50:51], v[22:23], v[50:51], v[30:31]
	v_pk_fma_f32 v[48:49], v[20:21], v[48:49], v[28:29]
	global_store_dwordx2 v[80:81], v[92:93], off offset:512
	v_cvt_pk_bf16_f32 v92, v52, v53
	v_cvt_pk_bf16_f32 v93, v54, v55
	v_cvt_pk_bf16_f32 v82, v48, v49
	v_cvt_pk_bf16_f32 v83, v50, v51
	s_andn2_b64 vcc, exec, s[34:35]
	global_store_dwordx2 v[80:81], v[92:93], off offset:1024
	global_store_dwordx2 v[80:81], v[82:83], off offset:1536
	s_cbranch_vccnz .LBB0_775
	v_cmp_lt_i32_e32 vcc, s57, v68
	s_mov_b64 s[18:19], 0
	s_and_saveexec_b64 s[36:37], vcc
	s_xor_b64 s[36:37], exec, s[36:37]
	s_cbranch_execnz .LBB0_779
	s_andn2_saveexec_b64 s[36:37], s[36:37]
	s_cbranch_execnz .LBB0_782
